# hg units: f/q tile loads issued at unit entry into spare VGPRs (moves behind a wait at first use)
# baseline (speedup 1.0000x reference)
.LBB0_649:
	s_andn2_b64 vcc, exec, s[42:43]
	s_cbranch_vccnz .LBB0_674
	s_and_b32 s45, s88, 3
	v_mov_b32_e32 v66, v186
	s_lshl_b32 s100, s44, 6
	v_and_b32_e32 v100, 63, v66
	v_or_b32_e32 v100, s100, v100
	v_mov_b64_e32 v[102:103], s[48:49]
	v_mad_u64_u32 v[102:103], vcc, v100, s13, v[102:103]
	s_mul_i32 s101, s45, 0xc0
	s_add_i32 s101, s101, 0x1400
	v_lshrrev_b32_e32 v104, 6, v66
	v_lshl_add_u32 v104, v104, 4, s101
	v_mov_b32_e32 v105, 0
	v_lshl_add_u64 v[102:103], v[102:103], 0, v[104:105]
	global_load_dwordx4 v[110:113], v[102:103], off
	global_load_dwordx4 v[114:117], v[102:103], off offset:128
	v_lshrrev_b32_e32 v106, 4, v66
	v_add_u32_e32 v106, s100, v106
	v_mov_b64_e32 v[108:109], s[48:49]
	v_mad_u64_u32 v[108:109], vcc, v106, s13, v[108:109]
	v_and_b32_e32 v107, 15, v66
	v_lshlrev_b32_e32 v107, 4, v107
	s_lshl_b32 s101, s45, 8
	s_addk_i32 s101, 0xc00
	v_add_u32_e32 v106, s101, v107
	v_mov_b32_e32 v107, 0
	v_lshl_add_u64 v[108:109], v[108:109], 0, v[106:107]
	v_add_co_u32_e32 v134, vcc, 0x3c000, v108
	s_nop 1
	v_addc_co_u32_e32 v135, vcc, 0, v109, vcc
	global_load_dwordx4 v[118:121], v[108:109], off offset:1024
	global_load_dwordx4 v[122:125], v[108:109], off
	global_load_dwordx4 v[126:129], v[134:135], off offset:1024
	global_load_dwordx4 v[130:133], v[134:135], off
	s_lshl_b32 s6, s45, 7
	s_mov_b64 s[42:43], -1
	s_and_b64 vcc, exec, s[4:5]
	v_lshlrev_b32_e32 v1, 3, v66
	s_cbranch_vccz .LBB0_652
	s_lshl_b32 s10, s6, 2
	v_readlane_b32 s11, v255, 31
	v_lshlrev_b32_e32 v0, 3, v66
	s_add_u32 s10, s11, s10
	v_readlane_b32 s11, v255, 32
	v_and_b32_e32 v140, 0x78, v0
	s_addc_u32 s11, s11, 0
	v_lshlrev_b32_e32 v2, 2, v140
	s_nop 1
	global_load_dwordx4 v[20:23], v2, s[10:11] offset:16
	global_load_dwordx4 v[24:27], v2, s[10:11]
	s_mov_b64 s[42:43], 0
	v_mov_b32_e32 v68, v140

.LBB0_654:
	s_lshl_b32 s10, s44, 2
	s_add_i32 s10, s88, s10
	s_add_i32 s12, s10, -4
	s_ashr_i32 s10, s12, 2
	s_ashr_i32 s11, s10, 31
	s_lshl_b64 s[46:47], s[10:11], 6
	s_mul_hi_i32 s11, s12, 0x6000
	s_mulk_i32 s12, 0x6000
	s_add_u32 s10, s33, s12
	s_addc_u32 s11, s57, s11
	v_lshlrev_b64 v[46:47], 1, v[140:141]
	v_and_b32_e32 v0, 0xffffff80, v0
	v_lshl_add_u64 v[2:3], s[10:11], 0, v[46:47]
	v_ashrrev_i32_e32 v1, 31, v0
	v_lshl_add_u64 v[4:5], v[0:1], 1, v[2:3]
	global_load_dwordx4 v[12:15], v[4:5], off
	v_add_u32_e32 v4, 0x1000, v0
	v_add_u32_e32 v0, 0x2000, v0
	v_ashrrev_i32_e32 v32, 3, v66
	v_ashrrev_i32_e32 v5, 31, v4
	v_ashrrev_i32_e32 v1, 31, v0
	v_ashrrev_i32_e32 v33, 31, v32
	v_lshl_add_u64 v[4:5], v[4:5], 1, v[2:3]
	v_lshl_add_u64 v[0:1], v[0:1], 1, v[2:3]
	v_lshl_add_u64 v[30:31], s[46:47], 0, v[32:33]
	v_mov_b64_e32 v[48:49], s[48:49]
	s_mulk_i32 s45, 0x60
	global_load_dwordx4 v[8:11], v[4:5], off
	v_and_b32_e32 v2, 7, v66
	global_load_dwordx4 v[4:7], v[0:1], off
	v_mad_u64_u32 v[0:1], s[10:11], v30, s13, v[48:49]
	v_mad_i32_i24 v1, v31, s13, v1
	s_lshl_b32 s60, s45, 1
	v_mul_u32_u24_e32 v33, 12, v2
	v_lshl_add_u64 v[0:1], v[0:1], 0, s[60:61]
	v_lshlrev_b32_e32 v140, 1, v33
	v_lshl_add_u64 v[0:1], v[0:1], 0, v[140:141]
	s_mov_b64 s[10:11], 0x1700
	s_movk_i32 s12, 0x1000
	v_lshl_add_u64 v[16:17], v[0:1], 0, s[10:11]
	v_add_co_u32_e32 v0, vcc, s12, v0
	v_ashrrev_i32_e32 v34, 4, v66
	s_nop 0
	v_addc_co_u32_e32 v1, vcc, 0, v1, vcc
	v_ashrrev_i32_e32 v35, 31, v34
	global_load_dwordx4 v[0:3], v[0:1], off offset:1792
	s_nop 0
	global_load_dwordx2 v[28:29], v[16:17], off offset:16
	v_lshl_add_u64 v[16:17], s[46:47], 0, v[34:35]
	v_mad_u64_u32 v[18:19], s[10:11], v16, s13, v[48:49]
	v_mad_i32_i24 v19, v17, s13, v19
	s_lshl_b32 s86, s6, 1
	s_mov_b32 s87, s61
	v_lshl_add_u64 v[16:17], v[18:19], 0, s[86:87]
	v_lshl_add_u64 v[16:17], v[16:17], 0, v[46:47]
	v_add_co_u32_e32 v18, vcc, s12, v16
	s_waitcnt vmcnt(0)
	v_pk_add_f32 v[50:51], v[24:25], 1.0 op_sel_hi:[1,0] neg_lo:[1,0] neg_hi:[1,0]
	v_addc_co_u32_e32 v19, vcc, 0, v17, vcc
	v_pk_add_f32 v[52:53], v[26:27], 1.0 op_sel_hi:[1,0] neg_lo:[1,0] neg_hi:[1,0]
	v_lshl_add_u32 v67, v68, 2, 0
	v_lshlrev_b32_e32 v35, 9, v34
	v_add_u32_e32 v35, v67, v35
	s_movk_i32 s6, 0x300
	s_waitcnt vmcnt(0)
	s_waitcnt vmcnt(0)
	v_mov_b32_e32 v36, v118
	v_mov_b32_e32 v37, v119
	v_mov_b32_e32 v38, v120
	v_mov_b32_e32 v39, v121
	v_lshlrev_b32_e32 v18, 16, v36
	v_and_b32_e32 v19, 0xffff0000, v36
	v_mul_f32_e32 v18, 0xbfb8aa3b, v18
	v_mul_f32_e32 v19, 0xbfb8aa3b, v19
	v_exp_f32_e32 v18, v18
	v_exp_f32_e32 v19, v19
	v_lshlrev_b32_e32 v42, 16, v37
	v_and_b32_e32 v43, 0xffff0000, v37
	v_lshlrev_b32_e32 v44, 16, v38
	v_pk_add_f32 v[18:19], v[18:19], 1.0 op_sel_hi:[1,0]
	v_and_b32_e32 v45, 0xffff0000, v38
	v_div_scale_f32 v36, s[10:11], v19, v19, 1.0
	v_rcp_f32_e32 v37, v36
	v_lshlrev_b32_e32 v56, 16, v39
	v_and_b32_e32 v60, 0xffff0000, v39
	v_fma_f32 v38, -v36, v37, 1.0
	v_fmac_f32_e32 v37, v38, v37
	v_div_scale_f32 v38, vcc, 1.0, v19, 1.0
	v_mul_f32_e32 v39, v38, v37
	v_fma_f32 v40, -v36, v39, v38
	v_fmac_f32_e32 v39, v40, v37
	v_fma_f32 v36, -v36, v39, v38
	v_div_fmas_f32 v36, v36, v37, v39
	v_div_fixup_f32 v19, v36, v19, 1.0
	v_div_scale_f32 v36, s[10:11], v18, v18, 1.0
	v_rcp_f32_e32 v37, v36
	s_nop 0
	v_fma_f32 v38, -v36, v37, 1.0
	v_fmac_f32_e32 v37, v38, v37
	v_div_scale_f32 v38, vcc, 1.0, v18, 1.0
	v_mul_f32_e32 v39, v38, v37
	v_fma_f32 v40, -v36, v39, v38
	v_fmac_f32_e32 v39, v40, v37
	v_fma_f32 v36, -v36, v39, v38
	v_div_fmas_f32 v36, v36, v37, v39
	v_div_fixup_f32 v18, v36, v18, 1.0
	v_pk_fma_f32 v[36:37], v[50:51], v[18:19], v[24:25]
	s_nop 0
	v_cmp_gt_f32_e32 vcc, s78, v36
	s_nop 1
	v_cndmask_b32_e64 v18, 0, 32, vcc
	v_ldexp_f32 v18, v36, v18
	v_log_f32_e32 v18, v18
	s_nop 0
	v_mul_f32_e32 v19, 0x3f317217, v18
	v_fma_f32 v19, v18, s20, -v19
	v_fmac_f32_e32 v19, 0x3377d1cf, v18
	v_fmac_f32_e32 v19, 0x3f317217, v18
	v_cmp_lt_f32_e64 s[42:43], |v18|, s17
	s_nop 1
	v_cndmask_b32_e64 v18, v18, v19, s[42:43]
	v_cndmask_b32_e32 v19, 0, v203, vcc
	v_cmp_gt_f32_e32 vcc, s78, v37
	v_sub_f32_e32 v40, v18, v19
	s_nop 0
	v_cndmask_b32_e64 v18, 0, 32, vcc
	v_ldexp_f32 v18, v37, v18
	v_log_f32_e32 v18, v18
	s_nop 0
	v_mul_f32_e32 v19, 0x3f317217, v18
	v_fma_f32 v19, v18, s20, -v19
	v_fmac_f32_e32 v19, 0x3377d1cf, v18
	v_fmac_f32_e32 v19, 0x3f317217, v18
	v_cmp_lt_f32_e64 s[42:43], |v18|, s17
	s_nop 1
	v_cndmask_b32_e64 v18, v18, v19, s[42:43]
	v_cndmask_b32_e32 v19, 0, v203, vcc
	v_sub_f32_e32 v41, v18, v19
	v_mul_f32_e32 v18, 0xbfb8aa3b, v42
	v_mul_f32_e32 v19, 0xbfb8aa3b, v43
	v_exp_f32_e32 v18, v18
	v_exp_f32_e32 v19, v19
	s_nop 0
	v_pk_add_f32 v[18:19], v[18:19], 1.0 op_sel_hi:[1,0]
	s_nop 0
	v_div_scale_f32 v38, s[10:11], v19, v19, 1.0
	v_rcp_f32_e32 v39, v38
	s_nop 0
	v_fma_f32 v42, -v38, v39, 1.0
	v_fmac_f32_e32 v39, v42, v39
	v_div_scale_f32 v42, vcc, 1.0, v19, 1.0
	v_mul_f32_e32 v43, v42, v39
	v_fma_f32 v54, -v38, v43, v42
	v_fmac_f32_e32 v43, v54, v39
	v_fma_f32 v38, -v38, v43, v42
	v_div_fmas_f32 v38, v38, v39, v43
	v_div_fixup_f32 v19, v38, v19, 1.0
	v_div_scale_f32 v38, s[10:11], v18, v18, 1.0
	v_rcp_f32_e32 v39, v38
	s_nop 0
	v_fma_f32 v42, -v38, v39, 1.0
	v_fmac_f32_e32 v39, v42, v39
	v_div_scale_f32 v42, vcc, 1.0, v18, 1.0
	v_mul_f32_e32 v43, v42, v39
	v_fma_f32 v54, -v38, v43, v42
	v_fmac_f32_e32 v43, v54, v39
	v_fma_f32 v38, -v38, v43, v42
	v_div_fmas_f32 v38, v38, v39, v43
	v_div_fixup_f32 v18, v38, v18, 1.0
	v_pk_fma_f32 v[38:39], v[52:53], v[18:19], v[26:27]
	v_pk_add_f32 v[54:55], v[20:21], 1.0 op_sel_hi:[1,0] neg_lo:[1,0] neg_hi:[1,0]
	v_cmp_gt_f32_e32 vcc, s78, v38
	s_nop 1
	v_cndmask_b32_e64 v18, 0, 32, vcc
	v_ldexp_f32 v18, v38, v18
	v_log_f32_e32 v18, v18
	s_nop 0
	v_mul_f32_e32 v19, 0x3f317217, v18
	v_fma_f32 v19, v18, s20, -v19
	v_fmac_f32_e32 v19, 0x3377d1cf, v18
	v_fmac_f32_e32 v19, 0x3f317217, v18
	v_cmp_lt_f32_e64 s[42:43], |v18|, s17
	s_nop 1
	v_cndmask_b32_e64 v18, v18, v19, s[42:43]
	v_cndmask_b32_e32 v19, 0, v203, vcc
	v_cmp_gt_f32_e32 vcc, s78, v39
	v_sub_f32_e32 v42, v18, v19
	s_nop 0
	v_cndmask_b32_e64 v18, 0, 32, vcc
	v_ldexp_f32 v18, v39, v18
	v_log_f32_e32 v18, v18
	s_nop 0
	v_mul_f32_e32 v19, 0x3f317217, v18
	v_fma_f32 v19, v18, s20, -v19
	v_fmac_f32_e32 v19, 0x3377d1cf, v18
	v_fmac_f32_e32 v19, 0x3f317217, v18
	v_cmp_lt_f32_e64 s[42:43], |v18|, s17
	s_nop 1
	v_cndmask_b32_e64 v18, v18, v19, s[42:43]
	v_cndmask_b32_e32 v19, 0, v203, vcc
	v_sub_f32_e32 v43, v18, v19
	v_mul_f32_e32 v18, 0xbfb8aa3b, v44
	v_mul_f32_e32 v19, 0xbfb8aa3b, v45
	v_exp_f32_e32 v18, v18
	v_exp_f32_e32 v19, v19
	ds_write_b128 v35, v[40:43]
	v_pk_add_f32 v[18:19], v[18:19], 1.0 op_sel_hi:[1,0]
	s_nop 0
	v_div_scale_f32 v40, s[10:11], v19, v19, 1.0
	v_rcp_f32_e32 v41, v40
	s_nop 0
	v_fma_f32 v42, -v40, v41, 1.0
	v_fmac_f32_e32 v41, v42, v41
	v_div_scale_f32 v42, vcc, 1.0, v19, 1.0
	v_mul_f32_e32 v43, v42, v41
	v_fma_f32 v44, -v40, v43, v42
	v_fmac_f32_e32 v43, v44, v41
	v_fma_f32 v40, -v40, v43, v42
	v_div_fmas_f32 v40, v40, v41, v43
	v_div_fixup_f32 v19, v40, v19, 1.0
	v_div_scale_f32 v40, s[10:11], v18, v18, 1.0
	v_rcp_f32_e32 v41, v40
	s_nop 0
	v_fma_f32 v42, -v40, v41, 1.0
	v_fmac_f32_e32 v41, v42, v41
	v_div_scale_f32 v42, vcc, 1.0, v18, 1.0
	v_mul_f32_e32 v43, v42, v41
	v_fma_f32 v44, -v40, v43, v42
	v_fmac_f32_e32 v43, v44, v41
	v_fma_f32 v40, -v40, v43, v42
	v_div_fmas_f32 v40, v40, v41, v43
	v_div_fixup_f32 v18, v40, v18, 1.0
	v_pk_fma_f32 v[40:41], v[54:55], v[18:19], v[20:21]
	s_nop 0
	v_cmp_gt_f32_e32 vcc, s78, v40
	s_nop 1
	v_cndmask_b32_e64 v18, 0, 32, vcc
	v_ldexp_f32 v18, v40, v18
	v_log_f32_e32 v18, v18
	s_nop 0
	v_mul_f32_e32 v19, 0x3f317217, v18
	v_fma_f32 v19, v18, s20, -v19
	v_fmac_f32_e32 v19, 0x3377d1cf, v18
	v_fmac_f32_e32 v19, 0x3f317217, v18
	v_cmp_lt_f32_e64 s[42:43], |v18|, s17
	s_nop 1
	v_cndmask_b32_e64 v18, v18, v19, s[42:43]
	v_cndmask_b32_e32 v19, 0, v203, vcc
	v_cmp_gt_f32_e32 vcc, s78, v41
	v_sub_f32_e32 v58, v18, v19
	s_nop 0
	v_cndmask_b32_e64 v18, 0, 32, vcc
	v_ldexp_f32 v18, v41, v18
	v_log_f32_e32 v18, v18
	s_nop 0
	v_mul_f32_e32 v19, 0x3f317217, v18
	v_fma_f32 v19, v18, s20, -v19
	v_fmac_f32_e32 v19, 0x3377d1cf, v18
	v_fmac_f32_e32 v19, 0x3f317217, v18
	v_cmp_lt_f32_e64 s[42:43], |v18|, s17
	s_nop 1
	v_cndmask_b32_e64 v18, v18, v19, s[42:43]
	v_cndmask_b32_e32 v19, 0, v203, vcc
	v_sub_f32_e32 v59, v18, v19
	v_mul_f32_e32 v18, 0xbfb8aa3b, v56
	v_mul_f32_e32 v19, 0xbfb8aa3b, v60
	v_exp_f32_e32 v18, v18
	v_exp_f32_e32 v19, v19
	v_pk_add_f32 v[56:57], v[22:23], 1.0 op_sel_hi:[1,0] neg_lo:[1,0] neg_hi:[1,0]
	v_pk_add_f32 v[18:19], v[18:19], 1.0 op_sel_hi:[1,0]
	s_nop 0
	v_div_scale_f32 v42, s[10:11], v19, v19, 1.0
	v_rcp_f32_e32 v43, v42
	s_nop 0
	v_fma_f32 v44, -v42, v43, 1.0
	v_fmac_f32_e32 v43, v44, v43
	v_div_scale_f32 v44, vcc, 1.0, v19, 1.0
	v_mul_f32_e32 v45, v44, v43
	v_fma_f32 v60, -v42, v45, v44
	v_fmac_f32_e32 v45, v60, v43
	v_fma_f32 v42, -v42, v45, v44
	v_div_fmas_f32 v42, v42, v43, v45
	v_div_fixup_f32 v19, v42, v19, 1.0
	v_div_scale_f32 v42, s[10:11], v18, v18, 1.0
	v_rcp_f32_e32 v43, v42
	s_nop 0
	v_fma_f32 v44, -v42, v43, 1.0
	v_fmac_f32_e32 v43, v44, v43
	v_div_scale_f32 v44, vcc, 1.0, v18, 1.0
	v_mul_f32_e32 v45, v44, v43
	v_fma_f32 v60, -v42, v45, v44
	v_fmac_f32_e32 v45, v60, v43
	v_fma_f32 v42, -v42, v45, v44
	v_div_fmas_f32 v42, v42, v43, v45
	v_div_fixup_f32 v18, v42, v18, 1.0
	v_pk_fma_f32 v[42:43], v[56:57], v[18:19], v[22:23]
	v_add_u32_e32 v44, 0x200, v66
	v_cmp_gt_f32_e32 vcc, s78, v42
	v_ashrrev_i32_e32 v44, 4, v44
	v_ashrrev_i32_e32 v45, 31, v44
	v_cndmask_b32_e64 v18, 0, 32, vcc
	v_ldexp_f32 v18, v42, v18
	v_log_f32_e32 v18, v18
	s_nop 0
	v_mul_f32_e32 v19, 0x3f317217, v18
	v_fma_f32 v19, v18, s20, -v19
	v_fmac_f32_e32 v19, 0x3377d1cf, v18
	v_fmac_f32_e32 v19, 0x3f317217, v18
	v_cmp_lt_f32_e64 s[42:43], |v18|, s17
	s_nop 1
	v_cndmask_b32_e64 v18, v18, v19, s[42:43]
	v_cndmask_b32_e32 v19, 0, v203, vcc
	v_cmp_gt_f32_e32 vcc, s78, v43
	v_sub_f32_e32 v60, v18, v19
	s_nop 0
	v_cndmask_b32_e64 v18, 0, 32, vcc
	v_ldexp_f32 v18, v43, v18
	v_log_f32_e32 v18, v18
	s_nop 0
	v_mul_f32_e32 v19, 0x3f317217, v18
	v_fma_f32 v19, v18, s20, -v19
	v_fmac_f32_e32 v19, 0x3377d1cf, v18
	v_fmac_f32_e32 v19, 0x3f317217, v18
	v_cmp_lt_f32_e64 s[42:43], |v18|, s17
	s_nop 1
	v_cndmask_b32_e64 v18, v18, v19, s[42:43]
	v_cndmask_b32_e32 v19, 0, v203, vcc
	v_sub_f32_e32 v61, v18, v19
	ds_write_b128 v35, v[58:61] offset:16
	v_lshl_add_u64 v[58:59], s[46:47], 0, v[44:45]
	v_mad_u64_u32 v[48:49], s[10:11], v58, s13, v[48:49]
	v_mad_i32_i24 v49, v59, s13, v49
	v_lshl_add_u64 v[48:49], v[48:49], 0, s[86:87]
	v_lshl_add_u64 v[58:59], v[48:49], 0, v[46:47]
	v_add_co_u32_e32 v46, vcc, s12, v58
	s_nop 0
	v_addc_co_u32_e32 v47, vcc, 0, v59, vcc
	v_lshlrev_b32_e32 v45, 9, v44
	v_add_u32_e32 v45, v67, v45
	s_waitcnt vmcnt(0)
	s_waitcnt vmcnt(0)
	v_mov_b32_e32 v46, v126
	v_mov_b32_e32 v47, v127
	v_mov_b32_e32 v48, v128
	v_mov_b32_e32 v49, v129
	v_lshlrev_b32_e32 v60, 16, v46
	v_and_b32_e32 v61, 0xffff0000, v46
	v_lshlrev_b32_e32 v62, 16, v47
	v_and_b32_e32 v63, 0xffff0000, v47
	v_mul_f32_e32 v46, 0xbfb8aa3b, v60
	v_mul_f32_e32 v47, 0xbfb8aa3b, v61
	v_exp_f32_e32 v46, v46
	v_exp_f32_e32 v47, v47
	v_lshlrev_b32_e32 v64, 16, v48
	v_and_b32_e32 v65, 0xffff0000, v48
	v_lshlrev_b32_e32 v69, 16, v49
	v_pk_add_f32 v[46:47], v[46:47], 1.0 op_sel_hi:[1,0]
	v_and_b32_e32 v70, 0xffff0000, v49
	v_div_scale_f32 v48, s[10:11], v47, v47, 1.0
	v_rcp_f32_e32 v49, v48
	s_nop 0
	v_fma_f32 v60, -v48, v49, 1.0
	v_fmac_f32_e32 v49, v60, v49
	v_div_scale_f32 v60, vcc, 1.0, v47, 1.0
	v_mul_f32_e32 v61, v60, v49
	v_fma_f32 v71, -v48, v61, v60
	v_fmac_f32_e32 v61, v71, v49
	v_fma_f32 v48, -v48, v61, v60
	v_div_fmas_f32 v48, v48, v49, v61
	v_div_fixup_f32 v47, v48, v47, 1.0
	v_div_scale_f32 v48, s[10:11], v46, v46, 1.0
	v_rcp_f32_e32 v49, v48
	s_nop 0
	v_fma_f32 v60, -v48, v49, 1.0
	v_fmac_f32_e32 v49, v60, v49
	v_div_scale_f32 v60, vcc, 1.0, v46, 1.0
	v_mul_f32_e32 v61, v60, v49
	v_fma_f32 v71, -v48, v61, v60
	v_fmac_f32_e32 v61, v71, v49
	v_fma_f32 v48, -v48, v61, v60
	v_div_fmas_f32 v48, v48, v49, v61
	v_div_fixup_f32 v46, v48, v46, 1.0
	v_pk_fma_f32 v[24:25], v[50:51], v[46:47], v[24:25]
	v_mul_f32_e32 v49, 0xbfb8aa3b, v63
	v_cmp_gt_f32_e32 vcc, s78, v24
	v_exp_f32_e32 v49, v49
	s_nop 0
	v_cndmask_b32_e64 v46, 0, 32, vcc
	v_ldexp_f32 v46, v24, v46
	v_log_f32_e32 v46, v46
	s_nop 0
	v_mul_f32_e32 v47, 0x3f317217, v46
	v_fma_f32 v47, v46, s20, -v47
	v_fmac_f32_e32 v47, 0x3377d1cf, v46
	v_fmac_f32_e32 v47, 0x3f317217, v46
	v_cmp_lt_f32_e64 s[42:43], |v46|, s17
	s_nop 1
	v_cndmask_b32_e64 v46, v46, v47, s[42:43]
	v_cndmask_b32_e32 v47, 0, v203, vcc
	v_cmp_gt_f32_e32 vcc, s78, v25
	v_sub_f32_e32 v46, v46, v47
	s_nop 0
	v_cndmask_b32_e64 v47, 0, 32, vcc
	v_ldexp_f32 v47, v25, v47
	v_log_f32_e32 v47, v47
	s_nop 0
	v_mul_f32_e32 v48, 0x3f317217, v47
	v_fma_f32 v48, v47, s20, -v48
	v_fmac_f32_e32 v48, 0x3377d1cf, v47
	v_fmac_f32_e32 v48, 0x3f317217, v47
	v_cmp_lt_f32_e64 s[42:43], |v47|, s17
	s_nop 1
	v_cndmask_b32_e64 v47, v47, v48, s[42:43]
	v_cndmask_b32_e32 v48, 0, v203, vcc
	v_sub_f32_e32 v47, v47, v48
	v_mul_f32_e32 v48, 0xbfb8aa3b, v62
	v_exp_f32_e32 v48, v48
	s_nop 0
	v_pk_add_f32 v[48:49], v[48:49], 1.0 op_sel_hi:[1,0]
	s_nop 0
	v_div_scale_f32 v50, s[10:11], v49, v49, 1.0
	v_rcp_f32_e32 v51, v50
	s_nop 0
	v_fma_f32 v60, -v50, v51, 1.0
	v_fmac_f32_e32 v51, v60, v51
	v_div_scale_f32 v60, vcc, 1.0, v49, 1.0
	v_mul_f32_e32 v61, v60, v51
	v_fma_f32 v62, -v50, v61, v60
	v_fmac_f32_e32 v61, v62, v51
	v_fma_f32 v50, -v50, v61, v60
	v_div_fmas_f32 v50, v50, v51, v61
	v_div_fixup_f32 v49, v50, v49, 1.0
	v_div_scale_f32 v50, s[10:11], v48, v48, 1.0
	v_rcp_f32_e32 v51, v50
	s_nop 0
	v_fma_f32 v60, -v50, v51, 1.0
	v_fmac_f32_e32 v51, v60, v51
	v_div_scale_f32 v60, vcc, 1.0, v48, 1.0
	v_mul_f32_e32 v61, v60, v51
	v_fma_f32 v62, -v50, v61, v60
	v_fmac_f32_e32 v61, v62, v51
	v_fma_f32 v50, -v50, v61, v60
	v_div_fmas_f32 v50, v50, v51, v61
	v_div_fixup_f32 v48, v50, v48, 1.0
	v_pk_fma_f32 v[26:27], v[52:53], v[48:49], v[26:27]
	s_nop 0
	v_cmp_gt_f32_e32 vcc, s78, v26
	s_nop 1
	v_cndmask_b32_e64 v48, 0, 32, vcc
	v_ldexp_f32 v48, v26, v48
	v_log_f32_e32 v48, v48
	s_nop 0
	v_mul_f32_e32 v49, 0x3f317217, v48
	v_fma_f32 v49, v48, s20, -v49
	v_fmac_f32_e32 v49, 0x3377d1cf, v48
	v_fmac_f32_e32 v49, 0x3f317217, v48
	v_cmp_lt_f32_e64 s[42:43], |v48|, s17
	s_nop 1
	v_cndmask_b32_e64 v48, v48, v49, s[42:43]
	v_cndmask_b32_e32 v49, 0, v203, vcc
	v_cmp_gt_f32_e32 vcc, s78, v27
	v_sub_f32_e32 v48, v48, v49
	s_nop 0
	v_cndmask_b32_e64 v49, 0, 32, vcc
	v_ldexp_f32 v49, v27, v49
	v_log_f32_e32 v49, v49
	s_nop 0
	v_mul_f32_e32 v50, 0x3f317217, v49
	v_fma_f32 v50, v49, s20, -v50
	v_fmac_f32_e32 v50, 0x3377d1cf, v49
	v_fmac_f32_e32 v50, 0x3f317217, v49
	v_cmp_lt_f32_e64 s[42:43], |v49|, s17
	s_nop 1
	v_cndmask_b32_e64 v49, v49, v50, s[42:43]
	v_cndmask_b32_e32 v50, 0, v203, vcc
	v_sub_f32_e32 v49, v49, v50
	ds_write_b128 v45, v[46:49]
	v_mul_f32_e32 v46, 0xbfb8aa3b, v64
	v_mul_f32_e32 v47, 0xbfb8aa3b, v65
	v_exp_f32_e32 v46, v46
	v_exp_f32_e32 v47, v47
	s_nop 0
	v_pk_add_f32 v[46:47], v[46:47], 1.0 op_sel_hi:[1,0]
	s_nop 0
	v_div_scale_f32 v48, s[10:11], v47, v47, 1.0
	v_rcp_f32_e32 v49, v48
	s_nop 0
	v_fma_f32 v50, -v48, v49, 1.0
	v_fmac_f32_e32 v49, v50, v49
	v_div_scale_f32 v50, vcc, 1.0, v47, 1.0
	v_mul_f32_e32 v51, v50, v49
	v_fma_f32 v52, -v48, v51, v50
	v_fmac_f32_e32 v51, v52, v49
	v_fma_f32 v48, -v48, v51, v50
	v_div_fmas_f32 v48, v48, v49, v51
	v_div_fixup_f32 v47, v48, v47, 1.0
	v_div_scale_f32 v48, s[10:11], v46, v46, 1.0
	v_rcp_f32_e32 v49, v48
	s_nop 0
	v_fma_f32 v50, -v48, v49, 1.0
	v_fmac_f32_e32 v49, v50, v49
	v_div_scale_f32 v50, vcc, 1.0, v46, 1.0
	v_mul_f32_e32 v51, v50, v49
	v_fma_f32 v52, -v48, v51, v50
	v_fmac_f32_e32 v51, v52, v49
	v_fma_f32 v48, -v48, v51, v50
	v_div_fmas_f32 v48, v48, v49, v51
	v_div_fixup_f32 v46, v48, v46, 1.0
	v_pk_fma_f32 v[46:47], v[54:55], v[46:47], v[20:21]
	v_mul_f32_e32 v49, 0xbfb8aa3b, v70
	v_cmp_gt_f32_e32 vcc, s78, v46
	v_exp_f32_e32 v49, v49
	s_nop 0
	v_cndmask_b32_e64 v20, 0, 32, vcc
	v_ldexp_f32 v20, v46, v20
	v_log_f32_e32 v20, v20
	s_nop 0
	v_mul_f32_e32 v21, 0x3f317217, v20
	v_fma_f32 v21, v20, s20, -v21
	v_fmac_f32_e32 v21, 0x3377d1cf, v20
	v_fmac_f32_e32 v21, 0x3f317217, v20
	v_cmp_lt_f32_e64 s[42:43], |v20|, s17
	s_nop 1
	v_cndmask_b32_e64 v20, v20, v21, s[42:43]
	v_cndmask_b32_e32 v21, 0, v203, vcc
	v_cmp_gt_f32_e32 vcc, s78, v47
	v_sub_f32_e32 v20, v20, v21
	s_nop 0
	v_cndmask_b32_e64 v21, 0, 32, vcc
	v_ldexp_f32 v21, v47, v21
	v_log_f32_e32 v21, v21
	s_nop 0
	v_mul_f32_e32 v48, 0x3f317217, v21
	v_fma_f32 v48, v21, s20, -v48
	v_fmac_f32_e32 v48, 0x3377d1cf, v21
	v_fmac_f32_e32 v48, 0x3f317217, v21
	v_cmp_lt_f32_e64 s[42:43], |v21|, s17
	s_nop 1
	v_cndmask_b32_e64 v21, v21, v48, s[42:43]
	v_cndmask_b32_e32 v48, 0, v203, vcc
	v_sub_f32_e32 v21, v21, v48
	v_mul_f32_e32 v48, 0xbfb8aa3b, v69
	v_exp_f32_e32 v48, v48
	s_nop 0
	v_pk_add_f32 v[48:49], v[48:49], 1.0 op_sel_hi:[1,0]
	s_nop 0
	v_div_scale_f32 v50, s[10:11], v49, v49, 1.0
	v_rcp_f32_e32 v51, v50
	s_nop 0
	v_fma_f32 v52, -v50, v51, 1.0
	v_fmac_f32_e32 v51, v52, v51
	v_div_scale_f32 v52, vcc, 1.0, v49, 1.0
	v_mul_f32_e32 v53, v52, v51
	v_fma_f32 v54, -v50, v53, v52
	v_fmac_f32_e32 v53, v54, v51
	v_fma_f32 v50, -v50, v53, v52
	v_div_fmas_f32 v50, v50, v51, v53
	v_div_fixup_f32 v49, v50, v49, 1.0
	v_div_scale_f32 v50, s[10:11], v48, v48, 1.0
	v_rcp_f32_e32 v51, v50
	s_nop 0
	v_fma_f32 v52, -v50, v51, 1.0
	v_fmac_f32_e32 v51, v52, v51
	v_div_scale_f32 v52, vcc, 1.0, v48, 1.0
	v_mul_f32_e32 v53, v52, v51
	v_fma_f32 v54, -v50, v53, v52
	v_fmac_f32_e32 v53, v54, v51
	v_fma_f32 v50, -v50, v53, v52
	v_div_fmas_f32 v50, v50, v51, v53
	v_div_fixup_f32 v48, v50, v48, 1.0
	v_pk_fma_f32 v[48:49], v[56:57], v[48:49], v[22:23]
	s_nop 0
	v_cmp_gt_f32_e32 vcc, s78, v48
	s_nop 1
	v_cndmask_b32_e64 v22, 0, 32, vcc
	v_ldexp_f32 v22, v48, v22
	v_log_f32_e32 v22, v22
	s_nop 0
	v_mul_f32_e32 v23, 0x3f317217, v22
	v_fma_f32 v23, v22, s20, -v23
	v_fmac_f32_e32 v23, 0x3377d1cf, v22
	v_fmac_f32_e32 v23, 0x3f317217, v22
	v_cmp_lt_f32_e64 s[42:43], |v22|, s17
	s_nop 1
	v_cndmask_b32_e64 v22, v22, v23, s[42:43]
	v_cndmask_b32_e32 v23, 0, v203, vcc
	v_cmp_gt_f32_e32 vcc, s78, v49
	v_sub_f32_e32 v22, v22, v23
	s_nop 0
	v_cndmask_b32_e64 v23, 0, 32, vcc
	v_ldexp_f32 v23, v49, v23
	v_log_f32_e32 v23, v23
	s_nop 0
	v_mul_f32_e32 v50, 0x3f317217, v23
	v_fma_f32 v50, v23, s20, -v50
	v_fmac_f32_e32 v50, 0x3377d1cf, v23
	v_fmac_f32_e32 v50, 0x3f317217, v23
	v_cmp_lt_f32_e64 s[42:43], |v23|, s17
	s_nop 1
	v_cndmask_b32_e64 v23, v23, v50, s[42:43]
	v_cndmask_b32_e32 v50, 0, v203, vcc
	v_sub_f32_e32 v23, v23, v50
	ds_write_b128 v45, v[20:23] offset:16
	v_cmp_gt_i32_e32 vcc, s6, v66
	s_and_saveexec_b64 s[42:43], vcc
	s_cbranch_execz .LBB0_657
	v_and_b32_e32 v52, 63, v66
	v_or_b32_e32 v53, s46, v52
	v_mov_b64_e32 v[50:51], s[48:49]
	v_mad_u64_u32 v[50:51], s[10:11], v53, s13, v[50:51]
	v_mad_i32_i24 v51, s47, v204, v51
	v_lshl_add_u64 v[50:51], v[50:51], 0, s[60:61]
	s_mov_b64 s[10:11], 0x1400
	v_readlane_b32 s6, v254, 61
	v_lshl_add_u64 v[50:51], v[50:51], 0, s[10:11]
	s_mov_b64 s[46:47], 0
	v_lshl_add_u32 v52, v52, 1, s6
	v_mov_b32_e32 v53, v66
	s_waitcnt vmcnt(0)

.LBB0_665:
	s_or_b64 exec, exec, s[42:43]
	v_pk_add_f32 v[50:51], v[38:39], 1.0 op_sel_hi:[1,0] neg_lo:[1,0] neg_hi:[1,0]
	v_pk_add_f32 v[38:39], v[40:41], 1.0 op_sel_hi:[1,0] neg_lo:[1,0] neg_hi:[1,0]
	s_waitcnt vmcnt(0)
	v_mov_b32_e32 v16, v122
	v_mov_b32_e32 v17, v123
	v_mov_b32_e32 v18, v124
	v_mov_b32_e32 v19, v125
	v_lshlrev_b32_e32 v40, 16, v16
	v_and_b32_e32 v41, 0xffff0000, v16
	v_mul_f32_e32 v54, 0xbfb8aa3b, v40
	v_mul_f32_e32 v55, 0xbfb8aa3b, v41
	v_exp_f32_e32 v54, v54
	v_exp_f32_e32 v55, v55
	v_lshlrev_b32_e32 v16, 16, v17
	v_and_b32_e32 v17, 0xffff0000, v17
	v_add_f32_e32 v54, 1.0, v54
	v_add_f32_e32 v55, 1.0, v55
	v_rcp_f32_e32 v54, v54
	v_rcp_f32_e32 v55, v55
	v_pk_add_f32 v[52:53], v[36:37], 1.0 op_sel_hi:[1,0] neg_lo:[1,0] neg_hi:[1,0]
	v_pk_add_f32 v[36:37], v[42:43], 1.0 op_sel_hi:[1,0] neg_lo:[1,0] neg_hi:[1,0]
	v_lshlrev_b32_e32 v42, 16, v18
	v_pk_mul_f32 v[54:55], v[54:55], v[40:41]
	v_mul_f32_e32 v40, 0xbfb8aa3b, v16
	v_mul_f32_e32 v41, 0xbfb8aa3b, v17
	v_exp_f32_e32 v40, v40
	v_exp_f32_e32 v41, v41
	v_and_b32_e32 v43, 0xffff0000, v18
	v_lshlrev_b32_e32 v18, 16, v19
	v_add_f32_e32 v40, 1.0, v40
	v_add_f32_e32 v41, 1.0, v41
	v_rcp_f32_e32 v40, v40
	v_rcp_f32_e32 v41, v41
	v_and_b32_e32 v19, 0xffff0000, v19
	s_waitcnt lgkmcnt(0)
	s_barrier
	v_pk_mul_f32 v[56:57], v[40:41], v[16:17]
	v_mul_f32_e32 v16, 0xbfb8aa3b, v42
	v_mul_f32_e32 v17, 0xbfb8aa3b, v43
	v_exp_f32_e32 v16, v16
	v_exp_f32_e32 v17, v17
	v_pk_add_f32 v[40:41], v[24:25], 1.0 op_sel_hi:[1,0] neg_lo:[1,0] neg_hi:[1,0]
	v_pk_add_f32 v[24:25], v[26:27], 1.0 op_sel_hi:[1,0] neg_lo:[1,0] neg_hi:[1,0]
	v_add_f32_e32 v16, 1.0, v16
	v_add_f32_e32 v17, 1.0, v17
	v_rcp_f32_e32 v16, v16
	v_rcp_f32_e32 v17, v17
	s_waitcnt vmcnt(0)
	s_waitcnt vmcnt(0)
	v_mov_b32_e32 v20, v130
	v_mov_b32_e32 v21, v131
	v_mov_b32_e32 v22, v132
	v_mov_b32_e32 v23, v133
	v_lshlrev_b32_e32 v26, 16, v20
	v_and_b32_e32 v27, 0xffff0000, v20
	v_pk_mul_f32 v[58:59], v[16:17], v[42:43]
	v_mul_f32_e32 v16, 0xbfb8aa3b, v18
	v_mul_f32_e32 v17, 0xbfb8aa3b, v19
	v_exp_f32_e32 v16, v16
	v_exp_f32_e32 v17, v17
	v_mul_f32_e32 v42, 0xbfb8aa3b, v26
	v_mul_f32_e32 v43, 0xbfb8aa3b, v27
	v_exp_f32_e32 v42, v42
	v_exp_f32_e32 v43, v43
	ds_read_b128 v[62:65], v67 offset:15872
	ds_read_b128 v[70:73], v67 offset:15888
	ds_read_b128 v[74:77], v35
	ds_read_b128 v[78:81], v35 offset:16
	v_add_f32_e32 v16, 1.0, v16
	v_add_f32_e32 v17, 1.0, v17
	v_rcp_f32_e32 v16, v16
	v_rcp_f32_e32 v17, v17
	v_add_f32_e32 v42, 1.0, v42
	v_add_f32_e32 v43, 1.0, v43
	s_waitcnt lgkmcnt(1)
	v_sub_f32_e32 v35, v74, v62
	v_rcp_f32_e32 v42, v42
	v_rcp_f32_e32 v43, v43
	v_mul_f32_e32 v35, 0x3fb8aa3b, v35
	v_pk_mul_f32 v[60:61], v[16:17], v[18:19]
	v_pk_add_f32 v[16:17], v[48:49], 1.0 op_sel_hi:[1,0] neg_lo:[1,0] neg_hi:[1,0]
	v_exp_f32_e32 v48, v35
	v_sub_f32_e32 v35, v62, v74
	v_mul_f32_e32 v35, 0x3fb8aa3b, v35
	v_lshlrev_b32_e32 v20, 16, v21
	v_and_b32_e32 v21, 0xffff0000, v21
	v_exp_f32_e32 v62, v35
	v_sub_f32_e32 v35, v75, v63
	v_pk_mul_f32 v[26:27], v[42:43], v[26:27]
	v_mul_f32_e32 v42, 0xbfb8aa3b, v20
	v_mul_f32_e32 v43, 0xbfb8aa3b, v21
	v_mul_f32_e32 v35, 0x3fb8aa3b, v35
	v_exp_f32_e32 v42, v42
	v_exp_f32_e32 v43, v43
	v_exp_f32_e32 v49, v35
	v_sub_f32_e32 v35, v63, v75
	v_mul_f32_e32 v35, 0x3fb8aa3b, v35
	v_exp_f32_e32 v63, v35
	v_sub_f32_e32 v35, v76, v64
	v_mul_f32_e32 v35, 0x3fb8aa3b, v35
	v_add_f32_e32 v42, 1.0, v42
	v_add_f32_e32 v43, 1.0, v43
	v_pk_mul_f32 v[74:75], v[54:55], v[48:49]
	v_pk_mul_f32 v[82:83], v[52:53], v[48:49]
	v_exp_f32_e32 v48, v35
	v_sub_f32_e32 v35, v64, v76
	v_rcp_f32_e32 v42, v42
	v_rcp_f32_e32 v43, v43
	v_mul_f32_e32 v35, 0x3fb8aa3b, v35
	v_pk_mul_f32 v[54:55], v[54:55], v[62:63]
	v_pk_mul_f32 v[62:63], v[52:53], v[62:63]
	v_exp_f32_e32 v52, v35
	v_sub_f32_e32 v35, v77, v65
	v_mul_f32_e32 v35, 0x3fb8aa3b, v35
	v_pk_add_f32 v[18:19], v[46:47], 1.0 op_sel_hi:[1,0] neg_lo:[1,0] neg_hi:[1,0]
	v_lshlrev_b32_e32 v46, 16, v22
	v_and_b32_e32 v47, 0xffff0000, v22
	v_exp_f32_e32 v49, v35
	v_sub_f32_e32 v35, v65, v77
	v_pk_mul_f32 v[42:43], v[42:43], v[20:21]
	v_mul_f32_e32 v20, 0xbfb8aa3b, v46
	v_mul_f32_e32 v21, 0xbfb8aa3b, v47
	v_mul_f32_e32 v35, 0x3fb8aa3b, v35
	v_exp_f32_e32 v20, v20
	v_exp_f32_e32 v21, v21
	v_exp_f32_e32 v53, v35
	s_waitcnt lgkmcnt(0)
	v_sub_f32_e32 v35, v78, v70
	v_mul_f32_e32 v35, 0x3fb8aa3b, v35
	v_pk_mul_f32 v[64:65], v[56:57], v[48:49]
	v_pk_mul_f32 v[84:85], v[50:51], v[48:49]
	v_exp_f32_e32 v48, v35
	v_sub_f32_e32 v35, v70, v78
	v_mul_f32_e32 v35, 0x3fb8aa3b, v35
	v_add_f32_e32 v20, 1.0, v20
	v_add_f32_e32 v21, 1.0, v21
	v_pk_mul_f32 v[76:77], v[56:57], v[52:53]
	v_pk_mul_f32 v[50:51], v[50:51], v[52:53]
	v_exp_f32_e32 v52, v35
	v_sub_f32_e32 v35, v79, v71
	v_rcp_f32_e32 v20, v20
	v_rcp_f32_e32 v21, v21
	v_mul_f32_e32 v35, 0x3fb8aa3b, v35
	v_exp_f32_e32 v49, v35
	v_sub_f32_e32 v35, v71, v79
	v_mul_f32_e32 v35, 0x3fb8aa3b, v35
	v_lshlrev_b32_e32 v22, 16, v23
	v_and_b32_e32 v23, 0xffff0000, v23
	v_exp_f32_e32 v53, v35
	v_pk_mul_f32 v[20:21], v[20:21], v[46:47]
	v_mul_f32_e32 v46, 0xbfb8aa3b, v22
	v_mul_f32_e32 v47, 0xbfb8aa3b, v23
	v_exp_f32_e32 v46, v46
	v_exp_f32_e32 v47, v47
	v_sub_f32_e32 v35, v80, v72
	v_mul_f32_e32 v35, 0x3fb8aa3b, v35
	v_pk_mul_f32 v[78:79], v[38:39], v[48:49]
	v_pk_mul_f32 v[86:87], v[38:39], v[52:53]
	v_exp_f32_e32 v38, v35
	v_sub_f32_e32 v35, v72, v80
	v_mul_f32_e32 v35, 0x3fb8aa3b, v35
	v_add_f32_e32 v46, 1.0, v46
	v_add_f32_e32 v47, 1.0, v47
	v_pk_mul_f32 v[70:71], v[58:59], v[48:49]
	v_exp_f32_e32 v48, v35
	v_sub_f32_e32 v35, v81, v73
	v_rcp_f32_e32 v46, v46
	v_rcp_f32_e32 v47, v47
	v_mul_f32_e32 v35, 0x3fb8aa3b, v35
	v_exp_f32_e32 v39, v35
	v_sub_f32_e32 v35, v73, v81
	v_mul_f32_e32 v35, 0x3fb8aa3b, v35
	v_exp_f32_e32 v49, v35
	v_pk_mul_f32 v[22:23], v[46:47], v[22:23]
	v_lshlrev_b32_e32 v47, 1, v68
	v_readlane_b32 s6, v254, 63
	v_pk_mul_f32 v[72:73], v[60:61], v[38:39]
	v_add_u32_e32 v68, 0, v47
	v_add_u32_e32 v90, s6, v47
	s_movk_i32 s6, 0x110
	v_pk_mul_f32 v[80:81], v[36:37], v[38:39]
	v_cvt_pk_bf16_f32 v39, v72, v73
	v_mul_lo_u32 v72, v34, s6
	v_pk_mul_f32 v[58:59], v[58:59], v[52:53]
	v_pk_mul_f32 v[60:61], v[60:61], v[48:49]
	v_pk_mul_f32 v[88:89], v[36:37], v[48:49]
	v_cvt_pk_bf16_f32 v36, v74, v75
	v_cvt_pk_bf16_f32 v37, v64, v65
	v_cvt_pk_bf16_f32 v38, v70, v71
	v_add_u32_e32 v34, v68, v72
	v_add_u32_e32 v91, s62, v47
	v_cvt_pk_bf16_f32 v48, v54, v55
	v_cvt_pk_bf16_f32 v52, v82, v83
	v_cvt_pk_bf16_f32 v49, v76, v77
	v_cvt_pk_bf16_f32 v53, v84, v85
	v_cvt_pk_bf16_f32 v57, v50, v51
	v_cvt_pk_bf16_f32 v50, v58, v59
	v_cvt_pk_bf16_f32 v54, v78, v79
	v_cvt_pk_bf16_f32 v51, v60, v61
	v_cvt_pk_bf16_f32 v55, v80, v81
	ds_write_b128 v34, v[36:39] offset:32768
	ds_write_b128 v34, v[48:51] offset:50176
	v_add_u32_e32 v34, v90, v72
	v_cvt_pk_bf16_f32 v56, v62, v63
	v_cvt_pk_bf16_f32 v58, v86, v87
	v_cvt_pk_bf16_f32 v59, v88, v89
	ds_write_b128 v34, v[52:55]
	v_add_u32_e32 v34, v91, v72
	ds_write_b128 v34, v[56:59]
	ds_read_b128 v[34:37], v67 offset:15872
	ds_read_b128 v[48:51], v67 offset:15888
	ds_read_b128 v[52:55], v45
	ds_read_b128 v[56:59], v45 offset:16
	v_readlane_b32 s10, v255, 0
	v_ashrrev_i32_e32 v46, 6, v66
	s_waitcnt lgkmcnt(1)
	v_sub_f32_e32 v38, v52, v34
	v_sub_f32_e32 v34, v34, v52
	v_sub_f32_e32 v39, v53, v35
	v_sub_f32_e32 v35, v35, v53
	v_mul_f32_e32 v38, 0x3fb8aa3b, v38
	v_mul_f32_e32 v34, 0x3fb8aa3b, v34
	v_mul_f32_e32 v39, 0x3fb8aa3b, v39
	v_mul_f32_e32 v35, 0x3fb8aa3b, v35
	v_exp_f32_e32 v38, v38
	v_exp_f32_e32 v34, v34
	v_exp_f32_e32 v39, v39
	v_exp_f32_e32 v35, v35
	s_waitcnt lgkmcnt(0)
	v_sub_f32_e32 v45, v49, v57
	v_mul_f32_e32 v45, 0x3fb8aa3b, v45
	v_pk_mul_f32 v[52:53], v[26:27], v[38:39]
	v_pk_mul_f32 v[26:27], v[26:27], v[34:35]
	v_pk_mul_f32 v[38:39], v[40:41], v[38:39]
	v_pk_mul_f32 v[34:35], v[40:41], v[34:35]
	v_sub_f32_e32 v40, v54, v36
	v_sub_f32_e32 v36, v36, v54
	v_sub_f32_e32 v41, v55, v37
	v_sub_f32_e32 v37, v37, v55
	v_mul_f32_e32 v40, 0x3fb8aa3b, v40
	v_mul_f32_e32 v36, 0x3fb8aa3b, v36
	v_mul_f32_e32 v41, 0x3fb8aa3b, v41
	v_mul_f32_e32 v37, 0x3fb8aa3b, v37
	v_exp_f32_e32 v40, v40
	v_exp_f32_e32 v36, v36
	v_exp_f32_e32 v41, v41
	v_exp_f32_e32 v37, v37
	v_cvt_pk_bf16_f32 v34, v34, v35
	v_pk_mul_f32 v[54:55], v[42:43], v[40:41]
	v_pk_mul_f32 v[42:43], v[42:43], v[36:37]
	v_pk_mul_f32 v[40:41], v[24:25], v[40:41]
	v_pk_mul_f32 v[36:37], v[24:25], v[36:37]
	v_sub_f32_e32 v25, v48, v56
	v_mul_f32_e32 v25, 0x3fb8aa3b, v25
	v_sub_f32_e32 v24, v56, v48
	v_exp_f32_e32 v48, v25
	v_sub_f32_e32 v25, v57, v49
	v_mul_f32_e32 v24, 0x3fb8aa3b, v24
	v_mul_f32_e32 v25, 0x3fb8aa3b, v25
	v_exp_f32_e32 v24, v24
	v_exp_f32_e32 v25, v25
	v_exp_f32_e32 v49, v45
	v_cvt_pk_bf16_f32 v35, v36, v37
	v_pk_mul_f32 v[62:63], v[18:19], v[24:25]
	v_pk_mul_f32 v[60:61], v[20:21], v[48:49]
	v_pk_mul_f32 v[48:49], v[18:19], v[48:49]
	v_sub_f32_e32 v19, v50, v58
	v_mul_f32_e32 v19, 0x3fb8aa3b, v19
	v_pk_mul_f32 v[56:57], v[20:21], v[24:25]
	v_sub_f32_e32 v18, v58, v50
	v_exp_f32_e32 v20, v19
	v_sub_f32_e32 v19, v59, v51
	v_mul_f32_e32 v18, 0x3fb8aa3b, v18
	v_mul_f32_e32 v19, 0x3fb8aa3b, v19
	v_sub_f32_e32 v21, v51, v59
	v_exp_f32_e32 v18, v18
	v_exp_f32_e32 v19, v19
	v_mul_f32_e32 v21, 0x3fb8aa3b, v21
	v_exp_f32_e32 v21, v21
	v_cvt_pk_bf16_f32 v24, v38, v39
	v_pk_mul_f32 v[50:51], v[22:23], v[18:19]
	v_mul_lo_u32 v38, v44, s6
	v_pk_mul_f32 v[58:59], v[22:23], v[20:21]
	v_pk_mul_f32 v[64:65], v[16:17], v[18:19]
	v_pk_mul_f32 v[70:71], v[16:17], v[20:21]
	v_cvt_pk_bf16_f32 v16, v52, v53
	v_cvt_pk_bf16_f32 v17, v54, v55
	v_cvt_pk_bf16_f32 v18, v56, v57
	v_cvt_pk_bf16_f32 v19, v50, v51
	v_add_u32_e32 v39, v68, v38
	v_cvt_pk_bf16_f32 v20, v26, v27
	v_cvt_pk_bf16_f32 v21, v42, v43
	v_cvt_pk_bf16_f32 v25, v40, v41
	v_cvt_pk_bf16_f32 v22, v60, v61
	v_cvt_pk_bf16_f32 v26, v62, v63
	v_cvt_pk_bf16_f32 v23, v58, v59
	v_cvt_pk_bf16_f32 v27, v64, v65
	ds_write_b128 v39, v[16:19] offset:32768
	ds_write_b128 v39, v[20:23] offset:50176
	v_add_u32_e32 v16, v90, v38
	v_cvt_pk_bf16_f32 v36, v48, v49
	v_cvt_pk_bf16_f32 v37, v70, v71
	ds_write_b128 v16, v[24:27]
	v_add_u32_e32 v16, v91, v38
	ds_write_b128 v16, v[34:37]
	v_add_u32_e32 v25, 0x25a00, v67
	ds_read_b128 v[16:19], v25
	ds_read_b128 v[20:23], v25 offset:16
	v_lshlrev_b32_e32 v26, 16, v12
	v_and_b32_e32 v27, 0xffff0000, v12
	v_add_u32_e32 v24, s10, v47
	s_waitcnt lgkmcnt(1)
	v_pk_mul_f32 v[16:17], v[16:17], v[26:27]
	s_nop 0
	v_cvt_pk_bf16_f32 v12, v16, v17
	v_lshlrev_b32_e32 v16, 16, v13
	v_and_b32_e32 v17, 0xffff0000, v13
	v_pk_mul_f32 v[16:17], v[18:19], v[16:17]
	s_nop 0
	v_cvt_pk_bf16_f32 v13, v16, v17
	v_lshlrev_b32_e32 v16, 16, v14
	v_and_b32_e32 v17, 0xffff0000, v14
	s_waitcnt lgkmcnt(0)
	v_pk_mul_f32 v[16:17], v[20:21], v[16:17]
	v_lshlrev_b32_e32 v20, 16, v8
	v_cvt_pk_bf16_f32 v14, v16, v17
	v_lshlrev_b32_e32 v16, 16, v15
	v_and_b32_e32 v17, 0xffff0000, v15
	v_pk_mul_f32 v[16:17], v[22:23], v[16:17]
	v_and_b32_e32 v21, 0xffff0000, v8
	v_cvt_pk_bf16_f32 v15, v16, v17
	v_add_u32_e32 v16, v24, v72
	ds_write_b128 v16, v[12:15]
	ds_read_b128 v[12:15], v25
	ds_read_b128 v[16:19], v25 offset:16
	s_waitcnt lgkmcnt(1)
	v_pk_mul_f32 v[12:13], v[12:13], v[20:21]
	s_nop 0
	v_cvt_pk_bf16_f32 v8, v12, v13
	v_lshlrev_b32_e32 v12, 16, v9
	v_and_b32_e32 v13, 0xffff0000, v9
	v_pk_mul_f32 v[12:13], v[14:15], v[12:13]
	s_nop 0
	v_cvt_pk_bf16_f32 v9, v12, v13
	v_lshlrev_b32_e32 v12, 16, v10
	v_and_b32_e32 v13, 0xffff0000, v10
	s_waitcnt lgkmcnt(0)
	v_pk_mul_f32 v[12:13], v[16:17], v[12:13]
	v_lshlrev_b32_e32 v16, 16, v4
	v_cvt_pk_bf16_f32 v10, v12, v13
	v_lshlrev_b32_e32 v12, 16, v11
	v_and_b32_e32 v13, 0xffff0000, v11
	v_pk_mul_f32 v[12:13], v[18:19], v[12:13]
	v_and_b32_e32 v17, 0xffff0000, v4
	v_cvt_pk_bf16_f32 v11, v12, v13
	v_add_u32_e32 v12, v24, v38
	ds_write_b128 v12, v[8:11]
	ds_read_b128 v[8:11], v25
	ds_read_b128 v[12:15], v25 offset:16
	v_add_u32_e32 v18, 0x400, v66
	s_waitcnt lgkmcnt(1)
	v_pk_mul_f32 v[8:9], v[8:9], v[16:17]
	s_nop 0
	v_cvt_pk_bf16_f32 v4, v8, v9
	v_lshlrev_b32_e32 v8, 16, v5
	v_and_b32_e32 v9, 0xffff0000, v5
	v_pk_mul_f32 v[8:9], v[10:11], v[8:9]
	v_mov_b32_e32 v10, 0
	v_cvt_pk_bf16_f32 v5, v8, v9
	v_lshlrev_b32_e32 v8, 16, v6
	v_and_b32_e32 v9, 0xffff0000, v6
	s_waitcnt lgkmcnt(0)
	v_pk_mul_f32 v[8:9], v[12:13], v[8:9]
	v_and_b32_e32 v13, 15, v66
	v_cvt_pk_bf16_f32 v6, v8, v9
	v_lshlrev_b32_e32 v8, 16, v7
	v_and_b32_e32 v9, 0xffff0000, v7
	v_pk_mul_f32 v[8:9], v[14:15], v[8:9]
	v_mov_b32_e32 v11, 0
	v_cvt_pk_bf16_f32 v7, v8, v9
	v_lshrrev_b32_e32 v8, 4, v18
	v_mad_u64_u32 v[8:9], s[10:11], v8, s6, v[24:25]
	ds_write_b128 v8, v[4:7]
	v_mul_u32_u24_e32 v5, 0x88, v13
	v_lshlrev_b32_e32 v4, 1, v46
	s_movk_i32 s6, 0x1100
	v_lshlrev_b32_e32 v14, 1, v5
	v_lshrrev_b32_e32 v5, 1, v66
	s_waitcnt lgkmcnt(0)
	s_barrier
	v_and_b32_e32 v20, 2, v4
	v_mul_lo_u32 v4, v69, s6
	v_and_b32_e32 v5, 24, v5
	v_add_u32_e32 v4, 0, v4
	v_lshlrev_b32_e32 v15, 1, v5
	v_add3_u32 v16, v4, v14, v15
	v_add3_u32 v17, s62, v14, v15
	v_cmp_ge_i32_e32 vcc, v69, v20
	v_mov_b32_e32 v4, 0
	v_mov_b32_e32 v8, 0
	v_mov_b32_e32 v9, 0
	s_and_saveexec_b64 s[42:43], vcc
	s_cbranch_execz .LBB0_667
	v_mad_u32_u24 v5, v20, s6, v17
	ds_read_b128 v[6:9], v16 offset:32768
	ds_read_b128 v[22:25], v5
	s_waitcnt lgkmcnt(0)
	v_mfma_f32_16x16x32_bf16 v[6:9], v[6:9], v[22:25], 0
	ds_read_b128 v[22:25], v16 offset:32832
	ds_read_b128 v[34:37], v5 offset:64
	s_waitcnt lgkmcnt(0)
	v_mfma_f32_16x16x32_bf16 v[6:9], v[22:25], v[34:37], v[6:9]
	ds_read_b128 v[22:25], v16 offset:32896
	ds_read_b128 v[34:37], v5 offset:128
	s_waitcnt lgkmcnt(0)
	v_mfma_f32_16x16x32_bf16 v[6:9], v[22:25], v[34:37], v[6:9]
	ds_read_b128 v[22:25], v16 offset:32960
	ds_read_b128 v[34:37], v5 offset:192
	s_waitcnt lgkmcnt(0)
	v_mfma_f32_16x16x32_bf16 v[8:11], v[22:25], v[34:37], v[6:9]

.LBB0_718:
	s_and_b64 vcc, exec, s[42:43]
	s_cbranch_vccz .LBB0_731
	s_lshl_b32 s6, s77, 1
	s_add_i32 s6, s86, s6
	s_add_i32 s52, s6, -2
	v_mov_b32_e32 v36, v186
	s_and_b32 s53, s52, 3
	s_ashr_i32 s100, s52, 2
	s_lshl_b32 s100, s100, 6
	v_and_b32_e32 v100, 63, v36
	v_or_b32_e32 v100, s100, v100
	v_mov_b64_e32 v[102:103], s[48:49]
	v_mad_u64_u32 v[102:103], vcc, v100, s13, v[102:103]
	s_mul_i32 s101, s53, 0xc0
	s_add_i32 s101, s101, 0x1400
	v_lshrrev_b32_e32 v104, 6, v36
	v_lshl_add_u32 v104, v104, 4, s101
	v_mov_b32_e32 v105, 0
	v_lshl_add_u64 v[102:103], v[102:103], 0, v[104:105]
	global_load_dwordx4 v[110:113], v[102:103], off
	global_load_dwordx4 v[114:117], v[102:103], off offset:128
	v_lshrrev_b32_e32 v106, 4, v36
	v_add_u32_e32 v106, s100, v106
	v_mov_b64_e32 v[108:109], s[48:49]
	v_mad_u64_u32 v[108:109], vcc, v106, s13, v[108:109]
	v_and_b32_e32 v107, 15, v36
	v_lshlrev_b32_e32 v107, 4, v107
	s_lshl_b32 s101, s53, 8
	s_addk_i32 s101, 0xc00
	v_add_u32_e32 v106, s101, v107
	v_mov_b32_e32 v107, 0
	v_lshl_add_u64 v[108:109], v[108:109], 0, v[106:107]
	v_add_co_u32_e32 v134, vcc, 0x3c000, v108
	s_nop 1
	v_addc_co_u32_e32 v135, vcc, 0, v109, vcc
	global_load_dwordx4 v[118:121], v[108:109], off offset:1024
	global_load_dwordx4 v[126:129], v[134:135], off offset:1024
	s_lshl_b32 s6, s53, 7
	v_lshlrev_b32_e32 v0, 3, v36
	s_mov_b64 s[42:43], -1
	s_and_b64 vcc, exec, s[4:5]
	v_and_b32_e32 v140, 0x78, v0
	s_cbranch_vccz .LBB0_721
	s_lshl_b32 s10, s6, 2
	v_readlane_b32 s11, v255, 31
	s_add_u32 s10, s11, s10
	v_readlane_b32 s11, v255, 32
	v_and_b32_e32 v24, 0x78, v0
	s_addc_u32 s11, s11, 0
	v_lshlrev_b32_e32 v0, 2, v24
	s_nop 1
	global_load_dwordx4 v[4:7], v0, s[10:11]
	s_nop 0
	global_load_dwordx4 v[0:3], v0, s[10:11] offset:16
	v_mov_b32_e32 v25, v141
	s_mov_b64 s[42:43], 0
	v_mov_b64_e32 v[8:9], v[24:25]

.LBB0_723:
	s_ashr_i32 s10, s52, 2
	s_ashr_i32 s11, s10, 31
	v_ashrrev_i32_e32 v28, 4, v36
	s_lshl_b64 s[54:55], s[10:11], 6
	v_ashrrev_i32_e32 v29, 31, v28
	v_lshl_add_u64 v[10:11], s[54:55], 0, v[28:29]
	v_mov_b64_e32 v[14:15], s[48:49]
	v_mad_u64_u32 v[12:13], s[10:11], v10, s13, v[14:15]
	v_mad_i32_i24 v13, v11, s13, v13
	s_lshl_b32 s60, s6, 1
	v_lshl_add_u64 v[10:11], v[12:13], 0, s[60:61]
	v_lshlrev_b64 v[22:23], 1, v[8:9]
	v_lshl_add_u64 v[8:9], v[10:11], 0, v[22:23]
	s_movk_i32 s6, 0x1000
	v_add_co_u32_e32 v8, vcc, s6, v8
	v_lshlrev_b32_e32 v26, 7, v28
	s_nop 0
	v_addc_co_u32_e32 v9, vcc, 0, v9, vcc
	s_add_i32 s58, 0, 0x10000
	s_waitcnt vmcnt(0)
	s_waitcnt vmcnt(0)
	v_mov_b32_e32 v8, v118
	v_mov_b32_e32 v9, v119
	v_mov_b32_e32 v10, v120
	v_mov_b32_e32 v11, v121
	v_lshlrev_b32_e32 v12, 16, v8
	v_and_b32_e32 v8, 0xffff0000, v8
	v_lshlrev_b32_e32 v20, 16, v11
	v_and_b32_e32 v21, 0xffff0000, v11
	v_or_b32_e32 v11, v24, v26
	v_lshlrev_b32_e32 v13, 16, v9
	v_lshlrev_b32_e32 v11, 2, v11
	v_mul_f32_e32 v8, 0xbfb8aa3b, v8
	v_and_b32_e32 v9, 0xffff0000, v9
	v_add_u32_e32 v31, s58, v11
	v_add_u32_e32 v27, 0, v11
	v_exp_f32_e32 v11, v8
	v_mul_f32_e32 v8, 0xbfb8aa3b, v13
	v_lshlrev_b32_e32 v16, 16, v10
	v_and_b32_e32 v17, 0xffff0000, v10
	v_mul_f32_e32 v10, 0xbfb8aa3b, v12
	v_exp_f32_e32 v12, v8
	v_mul_f32_e32 v8, 0xbfb8aa3b, v9
	v_exp_f32_e32 v13, v8
	v_mul_f32_e32 v8, 0xbfb8aa3b, v16
	v_exp_f32_e32 v18, v8
	v_mul_f32_e32 v8, 0xbfb8aa3b, v17
	v_exp_f32_e32 v19, v8
	v_mul_f32_e32 v8, 0xbfb8aa3b, v20
	v_exp_f32_e32 v20, v8
	v_mul_f32_e32 v8, 0xbfb8aa3b, v21
	v_exp_f32_e32 v21, v8
	v_add_u32_e32 v8, 0x200, v36
	v_ashrrev_i32_e32 v32, 4, v8
	v_ashrrev_i32_e32 v33, 31, v32
	v_lshl_add_u64 v[8:9], s[54:55], 0, v[32:33]
	v_mad_u64_u32 v[14:15], s[10:11], v8, s13, v[14:15]
	v_mad_i32_i24 v15, v9, s13, v15
	v_lshl_add_u64 v[8:9], v[14:15], 0, s[60:61]
	v_lshl_add_u64 v[8:9], v[8:9], 0, v[22:23]
	v_add_co_u32_e32 v8, vcc, s6, v8
	v_exp_f32_e32 v10, v10
	s_nop 0
	v_addc_co_u32_e32 v9, vcc, 0, v9, vcc
	v_lshlrev_b32_e32 v30, 7, v32
	v_pk_add_f32 v[10:11], v[10:11], 1.0 op_sel_hi:[1,0]
	v_pk_add_f32 v[12:13], v[12:13], 1.0 op_sel_hi:[1,0]
	s_movk_i32 s6, 0x300
	s_waitcnt vmcnt(0)
	s_waitcnt vmcnt(0)
	v_mov_b32_e32 v14, v126
	v_mov_b32_e32 v15, v127
	v_mov_b32_e32 v16, v128
	v_mov_b32_e32 v17, v129
	v_lshlrev_b32_e32 v8, 16, v14
	v_and_b32_e32 v9, 0xffff0000, v14
	v_or_b32_e32 v14, v24, v30
	v_lshlrev_b32_e32 v14, 2, v14
	v_add_u32_e32 v29, s58, v14
	v_add_u32_e32 v25, 0, v14
	v_div_scale_f32 v14, s[10:11], v11, v11, 1.0
	v_lshlrev_b32_e32 v35, 16, v15
	v_and_b32_e32 v34, 0xffff0000, v15
	v_rcp_f32_e32 v15, v14
	v_lshlrev_b32_e32 v39, 16, v16
	v_and_b32_e32 v38, 0xffff0000, v16
	v_lshlrev_b32_e32 v37, 16, v17
	v_fma_f32 v40, -v14, v15, 1.0
	v_fmac_f32_e32 v15, v40, v15
	v_div_scale_f32 v40, vcc, 1.0, v11, 1.0
	v_mul_f32_e32 v41, v40, v15
	v_fma_f32 v42, -v14, v41, v40
	v_fmac_f32_e32 v41, v42, v15
	v_fma_f32 v14, -v14, v41, v40
	v_div_fmas_f32 v14, v14, v15, v41
	v_div_fixup_f32 v11, v14, v11, 1.0
	v_div_scale_f32 v14, s[10:11], v10, v10, 1.0
	v_rcp_f32_e32 v15, v14
	v_and_b32_e32 v33, 0xffff0000, v17
	v_pk_add_f32 v[16:17], v[4:5], 1.0 op_sel_hi:[1,0] neg_lo:[1,0] neg_hi:[1,0]
	v_mul_f32_e32 v8, 0xbfb8aa3b, v8
	v_fma_f32 v40, -v14, v15, 1.0
	v_fmac_f32_e32 v15, v40, v15
	v_div_scale_f32 v40, vcc, 1.0, v10, 1.0
	v_mul_f32_e32 v41, v40, v15
	v_fma_f32 v42, -v14, v41, v40
	v_fmac_f32_e32 v41, v42, v15
	v_fma_f32 v14, -v14, v41, v40
	v_div_fmas_f32 v14, v14, v15, v41
	v_div_fixup_f32 v10, v14, v10, 1.0
	v_pk_fma_f32 v[40:41], v[16:17], v[10:11], v[4:5]
	v_mul_f32_e32 v9, 0xbfb8aa3b, v9
	v_cmp_gt_f32_e32 vcc, s78, v40
	v_exp_f32_e32 v8, v8
	v_exp_f32_e32 v9, v9
	v_cndmask_b32_e64 v10, 0, 32, vcc
	v_ldexp_f32 v10, v40, v10
	v_log_f32_e32 v10, v10
	v_pk_add_f32 v[14:15], v[40:41], 1.0 op_sel_hi:[1,0] neg_lo:[1,0] neg_hi:[1,0]
	v_pk_add_f32 v[8:9], v[8:9], 1.0 op_sel_hi:[1,0]
	v_mul_f32_e32 v11, 0x3f317217, v10
	v_fma_f32 v11, v10, s20, -v11
	v_fmac_f32_e32 v11, 0x3377d1cf, v10
	v_fmac_f32_e32 v11, 0x3f317217, v10
	v_cmp_lt_f32_e64 s[42:43], |v10|, s17
	s_nop 1
	v_cndmask_b32_e64 v10, v10, v11, s[42:43]
	v_cndmask_b32_e32 v11, 0, v203, vcc
	v_cmp_gt_f32_e32 vcc, s78, v41
	v_sub_f32_e32 v10, v10, v11
	s_nop 0
	v_cndmask_b32_e64 v11, 0, 32, vcc
	v_ldexp_f32 v11, v41, v11
	v_log_f32_e32 v11, v11
	s_nop 0
	v_mul_f32_e32 v40, 0x3f317217, v11
	v_fma_f32 v40, v11, s20, -v40
	v_fmac_f32_e32 v40, 0x3377d1cf, v11
	v_fmac_f32_e32 v40, 0x3f317217, v11
	v_cmp_lt_f32_e64 s[42:43], |v11|, s17
	s_nop 1
	v_cndmask_b32_e64 v11, v11, v40, s[42:43]
	v_cndmask_b32_e32 v40, 0, v203, vcc
	v_sub_f32_e32 v11, v11, v40
	v_div_scale_f32 v40, s[10:11], v9, v9, 1.0
	v_rcp_f32_e32 v41, v40
	s_nop 0
	v_fma_f32 v42, -v40, v41, 1.0
	v_fmac_f32_e32 v41, v42, v41
	v_div_scale_f32 v42, vcc, 1.0, v9, 1.0
	v_mul_f32_e32 v43, v42, v41
	v_fma_f32 v44, -v40, v43, v42
	v_fmac_f32_e32 v43, v44, v41
	v_fma_f32 v40, -v40, v43, v42
	v_div_fmas_f32 v40, v40, v41, v43
	v_div_fixup_f32 v9, v40, v9, 1.0
	v_div_scale_f32 v40, s[10:11], v8, v8, 1.0
	v_rcp_f32_e32 v41, v40
	s_nop 0
	v_fma_f32 v42, -v40, v41, 1.0
	v_fmac_f32_e32 v41, v42, v41
	v_div_scale_f32 v42, vcc, 1.0, v8, 1.0
	v_mul_f32_e32 v43, v42, v41
	v_fma_f32 v44, -v40, v43, v42
	v_fmac_f32_e32 v43, v44, v41
	v_fma_f32 v40, -v40, v43, v42
	v_div_fmas_f32 v40, v40, v41, v43
	v_div_fixup_f32 v8, v40, v8, 1.0
	v_pk_fma_f32 v[16:17], v[16:17], v[8:9], v[4:5]
	s_nop 0
	v_cmp_gt_f32_e32 vcc, s78, v16
	v_pk_add_f32 v[8:9], v[16:17], 1.0 op_sel_hi:[1,0] neg_lo:[1,0] neg_hi:[1,0]
	s_nop 0
	v_cndmask_b32_e64 v4, 0, 32, vcc
	v_ldexp_f32 v4, v16, v4
	v_log_f32_e32 v4, v4
	s_nop 0
	v_mul_f32_e32 v5, 0x3f317217, v4
	v_fma_f32 v5, v4, s20, -v5
	v_fmac_f32_e32 v5, 0x3377d1cf, v4
	v_fmac_f32_e32 v5, 0x3f317217, v4
	v_cmp_lt_f32_e64 s[42:43], |v4|, s17
	s_nop 1
	v_cndmask_b32_e64 v4, v4, v5, s[42:43]
	v_cndmask_b32_e32 v5, 0, v203, vcc
	v_cmp_gt_f32_e32 vcc, s78, v17
	v_sub_f32_e32 v4, v4, v5
	s_nop 0
	v_cndmask_b32_e64 v5, 0, 32, vcc
	v_ldexp_f32 v5, v17, v5
	v_log_f32_e32 v5, v5
	s_nop 0
	v_mul_f32_e32 v16, 0x3f317217, v5
	v_fma_f32 v16, v5, s20, -v16
	v_fmac_f32_e32 v16, 0x3377d1cf, v5
	v_fmac_f32_e32 v16, 0x3f317217, v5
	v_cmp_lt_f32_e64 s[42:43], |v5|, s17
	s_nop 1
	v_cndmask_b32_e64 v5, v5, v16, s[42:43]
	v_cndmask_b32_e32 v16, 0, v203, vcc
	v_sub_f32_e32 v5, v5, v16
	v_mul_f32_e32 v16, 0xbfb8aa3b, v35
	v_exp_f32_e32 v40, v16
	v_mul_f32_e32 v16, 0xbfb8aa3b, v34
	v_exp_f32_e32 v41, v16
	v_div_scale_f32 v16, s[10:11], v13, v13, 1.0
	v_rcp_f32_e32 v17, v16
	v_pk_add_f32 v[34:35], v[6:7], 1.0 op_sel_hi:[1,0] neg_lo:[1,0] neg_hi:[1,0]
	v_fma_f32 v42, -v16, v17, 1.0
	v_fmac_f32_e32 v17, v42, v17
	v_div_scale_f32 v42, vcc, 1.0, v13, 1.0
	v_mul_f32_e32 v43, v42, v17
	v_fma_f32 v44, -v16, v43, v42
	v_fmac_f32_e32 v43, v44, v17
	v_fma_f32 v16, -v16, v43, v42
	v_div_fmas_f32 v16, v16, v17, v43
	v_div_fixup_f32 v13, v16, v13, 1.0
	v_div_scale_f32 v16, s[10:11], v12, v12, 1.0
	v_rcp_f32_e32 v17, v16
	s_nop 0
	v_fma_f32 v42, -v16, v17, 1.0
	v_fmac_f32_e32 v17, v42, v17
	v_div_scale_f32 v42, vcc, 1.0, v12, 1.0
	v_mul_f32_e32 v43, v42, v17
	v_fma_f32 v44, -v16, v43, v42
	v_fmac_f32_e32 v43, v44, v17
	v_fma_f32 v16, -v16, v43, v42
	v_div_fmas_f32 v16, v16, v17, v43
	v_div_fixup_f32 v12, v16, v12, 1.0
	v_pk_fma_f32 v[42:43], v[34:35], v[12:13], v[6:7]
	s_nop 0
	v_cmp_gt_f32_e32 vcc, s78, v42
	v_pk_add_f32 v[16:17], v[42:43], 1.0 op_sel_hi:[1,0] neg_lo:[1,0] neg_hi:[1,0]
	ds_write_b128 v31, v[14:17]
	v_cndmask_b32_e64 v12, 0, 32, vcc
	v_ldexp_f32 v12, v42, v12
	v_log_f32_e32 v12, v12
	s_nop 0
	v_mul_f32_e32 v13, 0x3f317217, v12
	v_fma_f32 v13, v12, s20, -v13
	v_fmac_f32_e32 v13, 0x3377d1cf, v12
	v_fmac_f32_e32 v13, 0x3f317217, v12
	v_cmp_lt_f32_e64 s[42:43], |v12|, s17
	s_nop 1
	v_cndmask_b32_e64 v12, v12, v13, s[42:43]
	v_cndmask_b32_e32 v13, 0, v203, vcc
	v_cmp_gt_f32_e32 vcc, s78, v43
	v_sub_f32_e32 v12, v12, v13
	s_nop 0
	v_cndmask_b32_e64 v13, 0, 32, vcc
	v_ldexp_f32 v13, v43, v13
	v_log_f32_e32 v13, v13
	s_nop 0
	v_mul_f32_e32 v14, 0x3f317217, v13
	v_fma_f32 v14, v13, s20, -v14
	v_fmac_f32_e32 v14, 0x3377d1cf, v13
	v_fmac_f32_e32 v14, 0x3f317217, v13
	v_cmp_lt_f32_e64 s[42:43], |v13|, s17
	s_nop 1
	v_cndmask_b32_e64 v13, v13, v14, s[42:43]
	v_cndmask_b32_e32 v14, 0, v203, vcc
	v_sub_f32_e32 v13, v13, v14
	ds_write_b128 v27, v[10:13]
	v_pk_add_f32 v[10:11], v[40:41], 1.0 op_sel_hi:[1,0]
	s_nop 0
	v_div_scale_f32 v12, s[10:11], v11, v11, 1.0
	v_rcp_f32_e32 v13, v12
	s_nop 0
	v_fma_f32 v14, -v12, v13, 1.0
	v_fmac_f32_e32 v13, v14, v13
	v_div_scale_f32 v14, vcc, 1.0, v11, 1.0
	v_mul_f32_e32 v15, v14, v13
	v_fma_f32 v16, -v12, v15, v14
	v_fmac_f32_e32 v15, v16, v13
	v_fma_f32 v12, -v12, v15, v14
	v_div_fmas_f32 v12, v12, v13, v15
	v_div_fixup_f32 v11, v12, v11, 1.0
	v_div_scale_f32 v12, s[10:11], v10, v10, 1.0
	v_rcp_f32_e32 v13, v12
	s_nop 0
	v_fma_f32 v14, -v12, v13, 1.0
	v_fmac_f32_e32 v13, v14, v13
	v_div_scale_f32 v14, vcc, 1.0, v10, 1.0
	v_mul_f32_e32 v15, v14, v13
	v_fma_f32 v16, -v12, v15, v14
	v_fmac_f32_e32 v15, v16, v13
	v_fma_f32 v12, -v12, v15, v14
	v_div_fmas_f32 v12, v12, v13, v15
	v_div_fixup_f32 v10, v12, v10, 1.0
	v_pk_fma_f32 v[12:13], v[34:35], v[10:11], v[6:7]
	v_pk_add_f32 v[14:15], v[0:1], 1.0 op_sel_hi:[1,0] neg_lo:[1,0] neg_hi:[1,0]
	v_cmp_gt_f32_e32 vcc, s78, v12
	v_pk_add_f32 v[10:11], v[12:13], 1.0 op_sel_hi:[1,0] neg_lo:[1,0] neg_hi:[1,0]
	s_nop 0
	v_cndmask_b32_e64 v6, 0, 32, vcc
	v_ldexp_f32 v6, v12, v6
	v_log_f32_e32 v6, v6
	s_nop 0
	v_mul_f32_e32 v7, 0x3f317217, v6
	v_fma_f32 v7, v6, s20, -v7
	v_fmac_f32_e32 v7, 0x3377d1cf, v6
	v_fmac_f32_e32 v7, 0x3f317217, v6
	v_cmp_lt_f32_e64 s[42:43], |v6|, s17
	s_nop 1
	v_cndmask_b32_e64 v6, v6, v7, s[42:43]
	v_cndmask_b32_e32 v7, 0, v203, vcc
	v_cmp_gt_f32_e32 vcc, s78, v13
	v_sub_f32_e32 v6, v6, v7
	s_nop 0
	v_cndmask_b32_e64 v7, 0, 32, vcc
	v_ldexp_f32 v7, v13, v7
	v_log_f32_e32 v7, v7
	s_nop 0
	v_mul_f32_e32 v12, 0x3f317217, v7
	v_fma_f32 v12, v7, s20, -v12
	v_fmac_f32_e32 v12, 0x3377d1cf, v7
	v_fmac_f32_e32 v12, 0x3f317217, v7
	v_cmp_lt_f32_e64 s[42:43], |v7|, s17
	s_nop 1
	v_cndmask_b32_e64 v7, v7, v12, s[42:43]
	v_cndmask_b32_e32 v12, 0, v203, vcc
	v_sub_f32_e32 v7, v7, v12
	v_mul_f32_e32 v12, 0xbfb8aa3b, v39
	v_exp_f32_e32 v16, v12
	v_mul_f32_e32 v12, 0xbfb8aa3b, v38
	v_exp_f32_e32 v17, v12
	v_pk_add_f32 v[12:13], v[18:19], 1.0 op_sel_hi:[1,0]
	v_pk_add_f32 v[16:17], v[16:17], 1.0 op_sel_hi:[1,0]
	v_div_scale_f32 v18, s[10:11], v13, v13, 1.0
	v_rcp_f32_e32 v19, v18
	s_nop 0
	v_fma_f32 v34, -v18, v19, 1.0
	v_fmac_f32_e32 v19, v34, v19
	v_div_scale_f32 v34, vcc, 1.0, v13, 1.0
	v_mul_f32_e32 v35, v34, v19
	v_fma_f32 v38, -v18, v35, v34
	v_fmac_f32_e32 v35, v38, v19
	v_fma_f32 v18, -v18, v35, v34
	v_div_fmas_f32 v18, v18, v19, v35
	v_div_fixup_f32 v13, v18, v13, 1.0
	v_div_scale_f32 v18, s[10:11], v12, v12, 1.0
	v_rcp_f32_e32 v19, v18
	s_nop 0
	v_fma_f32 v34, -v18, v19, 1.0
	v_fmac_f32_e32 v19, v34, v19
	v_div_scale_f32 v34, vcc, 1.0, v12, 1.0
	v_mul_f32_e32 v35, v34, v19
	v_fma_f32 v38, -v18, v35, v34
	v_fmac_f32_e32 v35, v38, v19
	v_fma_f32 v18, -v18, v35, v34
	v_div_fmas_f32 v18, v18, v19, v35
	v_div_fixup_f32 v12, v18, v12, 1.0
	v_pk_fma_f32 v[34:35], v[14:15], v[12:13], v[0:1]
	s_nop 0
	v_cmp_gt_f32_e32 vcc, s78, v34
	v_pk_add_f32 v[18:19], v[34:35], 1.0 op_sel_hi:[1,0] neg_lo:[1,0] neg_hi:[1,0]
	s_nop 0
	v_cndmask_b32_e64 v12, 0, 32, vcc
	v_ldexp_f32 v12, v34, v12
	v_log_f32_e32 v12, v12
	s_nop 0
	v_mul_f32_e32 v13, 0x3f317217, v12
	v_fma_f32 v13, v12, s20, -v13
	v_fmac_f32_e32 v13, 0x3377d1cf, v12
	v_fmac_f32_e32 v13, 0x3f317217, v12
	v_cmp_lt_f32_e64 s[42:43], |v12|, s17
	s_nop 1
	v_cndmask_b32_e64 v12, v12, v13, s[42:43]
	v_cndmask_b32_e32 v13, 0, v203, vcc
	v_cmp_gt_f32_e32 vcc, s78, v35
	v_sub_f32_e32 v12, v12, v13
	s_nop 0
	v_cndmask_b32_e64 v13, 0, 32, vcc
	v_ldexp_f32 v13, v35, v13
	v_log_f32_e32 v13, v13
	s_nop 0
	v_mul_f32_e32 v34, 0x3f317217, v13
	v_fma_f32 v34, v13, s20, -v34
	v_fmac_f32_e32 v34, 0x3377d1cf, v13
	v_fmac_f32_e32 v34, 0x3f317217, v13
	v_cmp_lt_f32_e64 s[42:43], |v13|, s17
	s_nop 1
	v_cndmask_b32_e64 v13, v13, v34, s[42:43]
	v_cndmask_b32_e32 v34, 0, v203, vcc
	v_sub_f32_e32 v13, v13, v34
	v_div_scale_f32 v34, s[10:11], v17, v17, 1.0
	v_rcp_f32_e32 v35, v34
	s_nop 0
	v_fma_f32 v38, -v34, v35, 1.0
	v_fmac_f32_e32 v35, v38, v35
	v_div_scale_f32 v38, vcc, 1.0, v17, 1.0
	v_mul_f32_e32 v39, v38, v35
	v_fma_f32 v40, -v34, v39, v38
	v_fmac_f32_e32 v39, v40, v35
	v_fma_f32 v34, -v34, v39, v38
	v_div_fmas_f32 v34, v34, v35, v39
	v_div_fixup_f32 v17, v34, v17, 1.0
	v_div_scale_f32 v34, s[10:11], v16, v16, 1.0
	v_rcp_f32_e32 v35, v34
	s_nop 0
	v_fma_f32 v38, -v34, v35, 1.0
	v_fmac_f32_e32 v35, v38, v35
	v_div_scale_f32 v38, vcc, 1.0, v16, 1.0
	v_mul_f32_e32 v39, v38, v35
	v_fma_f32 v40, -v34, v39, v38
	v_fmac_f32_e32 v39, v40, v35
	v_fma_f32 v34, -v34, v39, v38
	v_div_fmas_f32 v34, v34, v35, v39
	v_div_fixup_f32 v16, v34, v16, 1.0
	v_pk_fma_f32 v[14:15], v[14:15], v[16:17], v[0:1]
	v_pk_add_f32 v[34:35], v[2:3], 1.0 op_sel_hi:[1,0] neg_lo:[1,0] neg_hi:[1,0]
	v_cmp_gt_f32_e32 vcc, s78, v14
	v_pk_add_f32 v[16:17], v[14:15], 1.0 op_sel_hi:[1,0] neg_lo:[1,0] neg_hi:[1,0]
	s_nop 0
	v_cndmask_b32_e64 v0, 0, 32, vcc
	v_ldexp_f32 v0, v14, v0
	v_log_f32_e32 v0, v0
	s_nop 0
	v_mul_f32_e32 v1, 0x3f317217, v0
	v_fma_f32 v1, v0, s20, -v1
	v_fmac_f32_e32 v1, 0x3377d1cf, v0
	v_fmac_f32_e32 v1, 0x3f317217, v0
	v_cmp_lt_f32_e64 s[42:43], |v0|, s17
	s_nop 1
	v_cndmask_b32_e64 v0, v0, v1, s[42:43]
	v_cndmask_b32_e32 v1, 0, v203, vcc
	v_cmp_gt_f32_e32 vcc, s78, v15
	v_sub_f32_e32 v0, v0, v1
	s_nop 0
	v_cndmask_b32_e64 v1, 0, 32, vcc
	v_ldexp_f32 v1, v15, v1
	v_log_f32_e32 v1, v1
	s_nop 0
	v_mul_f32_e32 v14, 0x3f317217, v1
	v_fma_f32 v14, v1, s20, -v14
	v_fmac_f32_e32 v14, 0x3377d1cf, v1
	v_fmac_f32_e32 v14, 0x3f317217, v1
	v_cmp_lt_f32_e64 s[42:43], |v1|, s17
	s_nop 1
	v_cndmask_b32_e64 v1, v1, v14, s[42:43]
	v_cndmask_b32_e32 v14, 0, v203, vcc
	v_sub_f32_e32 v1, v1, v14
	v_mul_f32_e32 v14, 0xbfb8aa3b, v37
	v_exp_f32_e32 v38, v14
	v_mul_f32_e32 v14, 0xbfb8aa3b, v33
	v_exp_f32_e32 v39, v14
	v_pk_add_f32 v[14:15], v[20:21], 1.0 op_sel_hi:[1,0]
	s_nop 0
	v_div_scale_f32 v20, s[10:11], v15, v15, 1.0
	v_rcp_f32_e32 v21, v20
	s_nop 0
	v_fma_f32 v33, -v20, v21, 1.0
	v_fmac_f32_e32 v21, v33, v21
	v_div_scale_f32 v33, vcc, 1.0, v15, 1.0
	v_mul_f32_e32 v37, v33, v21
	v_fma_f32 v40, -v20, v37, v33
	v_fmac_f32_e32 v37, v40, v21
	v_fma_f32 v20, -v20, v37, v33
	v_div_fmas_f32 v20, v20, v21, v37
	v_div_fixup_f32 v15, v20, v15, 1.0
	v_div_scale_f32 v20, s[10:11], v14, v14, 1.0
	v_rcp_f32_e32 v21, v20
	s_nop 0
	v_fma_f32 v33, -v20, v21, 1.0
	v_fmac_f32_e32 v21, v33, v21
	v_div_scale_f32 v33, vcc, 1.0, v14, 1.0
	v_mul_f32_e32 v37, v33, v21
	v_fma_f32 v40, -v20, v37, v33
	v_fmac_f32_e32 v37, v40, v21
	v_fma_f32 v20, -v20, v37, v33
	v_div_fmas_f32 v20, v20, v21, v37
	v_div_fixup_f32 v14, v20, v14, 1.0
	v_pk_fma_f32 v[40:41], v[34:35], v[14:15], v[2:3]
	s_nop 0
	v_cmp_gt_f32_e32 vcc, s78, v40
	v_pk_add_f32 v[20:21], v[40:41], 1.0 op_sel_hi:[1,0] neg_lo:[1,0] neg_hi:[1,0]
	ds_write_b128 v31, v[18:21] offset:16
	v_cndmask_b32_e64 v14, 0, 32, vcc
	v_ldexp_f32 v14, v40, v14
	v_log_f32_e32 v14, v14
	s_nop 0
	v_mul_f32_e32 v15, 0x3f317217, v14
	v_fma_f32 v15, v14, s20, -v15
	v_fmac_f32_e32 v15, 0x3377d1cf, v14
	v_fmac_f32_e32 v15, 0x3f317217, v14
	v_cmp_lt_f32_e64 s[42:43], |v14|, s17
	s_nop 1
	v_cndmask_b32_e64 v14, v14, v15, s[42:43]
	v_cndmask_b32_e32 v15, 0, v203, vcc
	v_cmp_gt_f32_e32 vcc, s78, v41
	v_sub_f32_e32 v14, v14, v15
	s_nop 0
	v_cndmask_b32_e64 v15, 0, 32, vcc
	v_ldexp_f32 v15, v41, v15
	v_log_f32_e32 v15, v15
	s_nop 0
	v_mul_f32_e32 v18, 0x3f317217, v15
	v_fma_f32 v18, v15, s20, -v18
	v_fmac_f32_e32 v18, 0x3377d1cf, v15
	v_fmac_f32_e32 v18, 0x3f317217, v15
	v_cmp_lt_f32_e64 s[42:43], |v15|, s17
	s_nop 1
	v_cndmask_b32_e64 v15, v15, v18, s[42:43]
	v_cndmask_b32_e32 v18, 0, v203, vcc
	v_sub_f32_e32 v15, v15, v18
	ds_write_b128 v27, v[12:15] offset:16
	ds_write_b128 v29, v[8:11]
	ds_write_b128 v25, v[4:7]
	v_pk_add_f32 v[4:5], v[38:39], 1.0 op_sel_hi:[1,0]
	s_nop 0
	v_div_scale_f32 v6, s[10:11], v5, v5, 1.0
	v_rcp_f32_e32 v7, v6
	s_nop 0
	v_fma_f32 v8, -v6, v7, 1.0
	v_fmac_f32_e32 v7, v8, v7
	v_div_scale_f32 v8, vcc, 1.0, v5, 1.0
	v_mul_f32_e32 v9, v8, v7
	v_fma_f32 v10, -v6, v9, v8
	v_fmac_f32_e32 v9, v10, v7
	v_fma_f32 v6, -v6, v9, v8
	v_div_fmas_f32 v6, v6, v7, v9
	v_div_fixup_f32 v5, v6, v5, 1.0
	v_div_scale_f32 v6, s[10:11], v4, v4, 1.0
	v_rcp_f32_e32 v7, v6
	s_nop 0
	v_fma_f32 v8, -v6, v7, 1.0
	v_fmac_f32_e32 v7, v8, v7
	v_div_scale_f32 v8, vcc, 1.0, v4, 1.0
	v_mul_f32_e32 v9, v8, v7
	v_fma_f32 v10, -v6, v9, v8
	v_fmac_f32_e32 v9, v10, v7
	v_fma_f32 v6, -v6, v9, v8
	v_div_fmas_f32 v6, v6, v7, v9
	v_div_fixup_f32 v4, v6, v4, 1.0
	v_pk_fma_f32 v[4:5], v[34:35], v[4:5], v[2:3]
	s_nop 0
	v_cmp_gt_f32_e32 vcc, s78, v4
	v_pk_add_f32 v[18:19], v[4:5], 1.0 op_sel_hi:[1,0] neg_lo:[1,0] neg_hi:[1,0]
	ds_write_b128 v29, v[16:19] offset:16
	v_cndmask_b32_e64 v2, 0, 32, vcc
	v_ldexp_f32 v2, v4, v2
	v_log_f32_e32 v2, v2
	s_nop 0
	v_mul_f32_e32 v3, 0x3f317217, v2
	v_fma_f32 v3, v2, s20, -v3
	v_fmac_f32_e32 v3, 0x3377d1cf, v2
	v_fmac_f32_e32 v3, 0x3f317217, v2
	v_cmp_lt_f32_e64 s[42:43], |v2|, s17
	s_nop 1
	v_cndmask_b32_e64 v2, v2, v3, s[42:43]
	v_cndmask_b32_e32 v3, 0, v203, vcc
	v_cmp_gt_f32_e32 vcc, s78, v5
	v_sub_f32_e32 v2, v2, v3
	s_nop 0
	v_cndmask_b32_e64 v3, 0, 32, vcc
	v_ldexp_f32 v3, v5, v3
	v_log_f32_e32 v3, v3
	s_nop 0
	v_mul_f32_e32 v4, 0x3f317217, v3
	v_fma_f32 v4, v3, s20, -v4
	v_fmac_f32_e32 v4, 0x3377d1cf, v3
	v_fmac_f32_e32 v4, 0x3f317217, v3
	v_cmp_lt_f32_e64 s[42:43], |v3|, s17
	s_nop 1
	v_cndmask_b32_e64 v3, v3, v4, s[42:43]
	v_cndmask_b32_e32 v4, 0, v203, vcc
	v_sub_f32_e32 v3, v3, v4
	v_cmp_gt_i32_e32 vcc, s6, v36
	ds_write_b128 v25, v[0:3] offset:16
	s_and_saveexec_b64 s[42:43], vcc
	s_cbranch_execz .LBB0_726
	v_and_b32_e32 v2, 63, v36
	v_or_b32_e32 v3, s54, v2
	v_mov_b64_e32 v[0:1], s[48:49]
	v_mad_u64_u32 v[0:1], s[10:11], v3, s13, v[0:1]
	v_mad_i32_i24 v1, s55, v204, v1
	s_mul_i32 s60, s53, 0xc0
	v_lshl_add_u64 v[0:1], v[0:1], 0, s[60:61]
	s_mov_b64 s[10:11], 0x1400
	v_lshl_add_u64 v[0:1], v[0:1], 0, s[10:11]
	v_lshl_add_u32 v2, v2, 1, 0
	s_mov_b64 s[54:55], 0
	v_mov_b32_e32 v3, v36
	s_waitcnt vmcnt(0)
